# P1+P8: accumulator zeroing (128 v_mov per unit) removed - first two phases of each unit's first K iteration peeled with C=0 on the first MFMA of every accumulator
# speedup vs baseline: 1.0036x; 1.0026x over previous
.LBB0_327:
	s_ashr_i32 s23, s22, 31
	s_lshl_b64 s[24:25], s[22:23], 19
	s_add_u32 s24, s72, s24
	s_addc_u32 s25, s73, s25
	s_and_b64 s[26:27], s[6:7], exec
	s_cselect_b32 s23, s25, s47
	s_cselect_b32 s56, s24, s46
	s_ashr_i32 s21, s20, 31
	s_lshl_b64 s[26:27], s[20:21], 19
	s_add_u32 s26, s0, s26
	s_addc_u32 s27, s1, s27
	s_and_b64 s[48:49], s[6:7], exec
	s_cselect_b32 s57, s27, s31
	s_cselect_b32 s58, s26, s30
	s_lshl_b32 s21, s28, 8
	v_add_u32_e32 v6, s21, v227
	s_add_u32 s28, s46, 0x3ff80
	v_ashrrev_i32_e32 v7, 31, v6
	s_addc_u32 s29, s47, 0
	v_lshl_add_u64 v[214:215], v[6:7], 4, s[16:17]
	s_add_u32 s59, s30, 0
	s_addc_u32 s60, s31, 0
	s_mov_b32 s61, -2
	v_add_u32_e32 v146, s53, v225
	v_add_u32_e32 v162, s54, v225
	ds_read_b128 v[134:137], v146
	ds_read_b128 v[138:141], v146 offset:1024
	ds_read_b128 v[142:145], v146 offset:2048
	ds_read_b128 v[146:149], v146 offset:3072
	ds_read_b128 v[150:153], v162
	ds_read_b128 v[154:157], v162 offset:1024
	ds_read_b128 v[158:161], v162 offset:2048
	ds_read_b128 v[162:165], v162 offset:3072
	ds_read_b128 v[166:169], v229
	ds_read_b128 v[170:173], v229 offset:1024
	ds_read_b128 v[174:177], v229 offset:2048
	ds_read_b128 v[178:181], v229 offset:3072
	ds_read_b128 v[182:185], v229 offset:4096
	ds_read_b128 v[186:189], v229 offset:5120
	ds_read_b128 v[190:193], v229 offset:6144
	ds_read_b128 v[194:197], v229 offset:7168
	s_add_u32 s28, s28, 0x100
	s_addc_u32 s29, s29, 0
	s_add_u32 s59, s59, 0x100
	s_addc_u32 s60, s60, 0
	s_cmp_eq_u32 s61, 12
	s_cselect_b64 s[30:31], -1, 0
	s_cbranch_scc0 .Lpeel1_332
	global_load_dwordx4 v[2:5], v[214:215], off
.Lpeel1_332:
	s_add_u32 s48, s28, 0xfffc0080
	s_addc_u32 s49, s29, -1
	s_and_b64 s[46:47], s[30:31], exec
	s_cselect_b32 s49, s23, s49
	s_cselect_b32 s48, s56, s48
	s_cselect_b32 s47, s57, s60
	s_cselect_b32 s46, s58, s59
	s_add_i32 m0, s40, 0xc000
	s_nop 0
	global_load_lds_dwordx4 v206, s[28:29]
	s_add_i32 m0, s40, 0xe000
	s_nop 0
	global_load_lds_dwordx4 v208, s[28:29]
	s_waitcnt vmcnt(8) lgkmcnt(0)
	s_barrier
	v_mfma_f32_16x16x32_bf16 v[130:133], v[134:137], v[166:169], 0
	v_mfma_f32_16x16x32_bf16 v[122:125], v[142:145], v[166:169], 0
	v_mfma_f32_16x16x32_bf16 v[114:117], v[134:137], v[174:177], 0
	v_mfma_f32_16x16x32_bf16 v[106:109], v[142:145], v[174:177], 0
	v_mfma_f32_16x16x32_bf16 v[98:101], v[134:137], v[182:185], 0
	v_mfma_f32_16x16x32_bf16 v[90:93], v[142:145], v[182:185], 0
	v_mfma_f32_16x16x32_bf16 v[82:85], v[134:137], v[190:193], 0
	v_mfma_f32_16x16x32_bf16 v[74:77], v[142:145], v[190:193], 0
	v_mfma_f32_16x16x32_bf16 v[130:133], v[138:141], v[170:173], v[130:133]
	v_mfma_f32_16x16x32_bf16 v[122:125], v[146:149], v[170:173], v[122:125]
	v_mfma_f32_16x16x32_bf16 v[114:117], v[138:141], v[178:181], v[114:117]
	v_mfma_f32_16x16x32_bf16 v[106:109], v[146:149], v[178:181], v[106:109]
	v_mfma_f32_16x16x32_bf16 v[98:101], v[138:141], v[186:189], v[98:101]
	v_mfma_f32_16x16x32_bf16 v[90:93], v[146:149], v[186:189], v[90:93]
	v_mfma_f32_16x16x32_bf16 v[82:85], v[138:141], v[194:197], v[82:85]
	v_mfma_f32_16x16x32_bf16 v[74:77], v[146:149], v[194:197], v[74:77]
	v_mfma_f32_16x16x32_bf16 v[126:129], v[150:153], v[166:169], 0
	v_mfma_f32_16x16x32_bf16 v[118:121], v[158:161], v[166:169], 0
	v_mfma_f32_16x16x32_bf16 v[110:113], v[150:153], v[174:177], 0
	v_mfma_f32_16x16x32_bf16 v[102:105], v[158:161], v[174:177], 0
	v_mfma_f32_16x16x32_bf16 v[94:97], v[150:153], v[182:185], 0
	v_mfma_f32_16x16x32_bf16 v[86:89], v[158:161], v[182:185], 0
	v_mfma_f32_16x16x32_bf16 v[78:81], v[150:153], v[190:193], 0
	v_mfma_f32_16x16x32_bf16 v[70:73], v[158:161], v[190:193], 0
	v_mfma_f32_16x16x32_bf16 v[126:129], v[154:157], v[170:173], v[126:129]
	v_mfma_f32_16x16x32_bf16 v[118:121], v[162:165], v[170:173], v[118:121]
	v_mfma_f32_16x16x32_bf16 v[110:113], v[154:157], v[178:181], v[110:113]
	v_mfma_f32_16x16x32_bf16 v[102:105], v[162:165], v[178:181], v[102:105]
	v_mfma_f32_16x16x32_bf16 v[94:97], v[154:157], v[186:189], v[94:97]
	v_mfma_f32_16x16x32_bf16 v[86:89], v[162:165], v[186:189], v[86:89]
	v_mfma_f32_16x16x32_bf16 v[78:81], v[154:157], v[194:197], v[78:81]
	v_mfma_f32_16x16x32_bf16 v[70:73], v[162:165], v[194:197], v[70:73]
	s_barrier
	ds_read_b128 v[166:169], v229 offset:16384
	ds_read_b128 v[170:173], v229 offset:17408
	ds_read_b128 v[174:177], v229 offset:18432
	ds_read_b128 v[178:181], v229 offset:19456
	ds_read_b128 v[182:185], v229 offset:20480
	ds_read_b128 v[186:189], v229 offset:21504
	ds_read_b128 v[190:193], v229 offset:22528
	ds_read_b128 v[194:197], v229 offset:23552
	s_add_i32 s62, s53, s12
	s_add_u32 s98, s46, s10
	s_addc_u32 s99, s47, s11
	s_mov_b32 m0, s62
	s_nop 0
	global_load_lds_dwordx4 v202, s[46:47]
	s_add_i32 m0, s62, 0x2000
	s_add_u32 s62, s46, 0x40000
	s_addc_u32 s63, s47, 0
	s_add_i32 s64, s54, s12
	global_load_lds_dwordx4 v198, s[46:47]
	s_mov_b32 m0, s64
	s_add_u32 s100, s48, s10
	s_addc_u32 s101, s49, s11
	global_load_lds_dwordx4 v202, s[62:63]
	s_add_i32 m0, s64, 0x2000
	s_nop 0
	global_load_lds_dwordx4 v198, s[62:63]
	s_mov_b32 m0, s40
	s_nop 0
	global_load_lds_dwordx4 v204, s[48:49]
	s_mov_b32 m0, s41
	s_nop 0
	global_load_lds_dwordx4 v200, s[48:49]
	s_waitcnt vmcnt(8) lgkmcnt(0)
	s_barrier
	v_mfma_f32_16x16x32_bf16 v[66:69], v[134:137], v[166:169], 0
	v_mfma_f32_16x16x32_bf16 v[58:61], v[142:145], v[166:169], 0
	v_mfma_f32_16x16x32_bf16 v[50:53], v[134:137], v[174:177], 0
	v_mfma_f32_16x16x32_bf16 v[42:45], v[142:145], v[174:177], 0
	v_mfma_f32_16x16x32_bf16 v[34:37], v[134:137], v[182:185], 0
	v_mfma_f32_16x16x32_bf16 v[26:29], v[142:145], v[182:185], 0
	v_mfma_f32_16x16x32_bf16 v[18:21], v[134:137], v[190:193], 0
	v_mfma_f32_16x16x32_bf16 v[10:13], v[142:145], v[190:193], 0
	v_mfma_f32_16x16x32_bf16 v[66:69], v[138:141], v[170:173], v[66:69]
	v_mfma_f32_16x16x32_bf16 v[58:61], v[146:149], v[170:173], v[58:61]
	v_mfma_f32_16x16x32_bf16 v[50:53], v[138:141], v[178:181], v[50:53]
	v_mfma_f32_16x16x32_bf16 v[42:45], v[146:149], v[178:181], v[42:45]
	v_mfma_f32_16x16x32_bf16 v[34:37], v[138:141], v[186:189], v[34:37]
	v_mfma_f32_16x16x32_bf16 v[26:29], v[146:149], v[186:189], v[26:29]
	v_mfma_f32_16x16x32_bf16 v[18:21], v[138:141], v[194:197], v[18:21]
	v_mfma_f32_16x16x32_bf16 v[10:13], v[146:149], v[194:197], v[10:13]
	v_mfma_f32_16x16x32_bf16 v[62:65], v[150:153], v[166:169], 0
	v_mfma_f32_16x16x32_bf16 v[54:57], v[158:161], v[166:169], 0
	v_mfma_f32_16x16x32_bf16 v[46:49], v[150:153], v[174:177], 0
	v_mfma_f32_16x16x32_bf16 v[38:41], v[158:161], v[174:177], 0
	v_mfma_f32_16x16x32_bf16 v[30:33], v[150:153], v[182:185], 0
	v_mfma_f32_16x16x32_bf16 v[22:25], v[158:161], v[182:185], 0
	v_mfma_f32_16x16x32_bf16 v[14:17], v[150:153], v[190:193], 0
	v_mfma_f32_16x16x32_bf16 v[6:9], v[158:161], v[190:193], 0
	v_mfma_f32_16x16x32_bf16 v[62:65], v[154:157], v[170:173], v[62:65]
	v_mfma_f32_16x16x32_bf16 v[54:57], v[162:165], v[170:173], v[54:57]
	v_mfma_f32_16x16x32_bf16 v[46:49], v[154:157], v[178:181], v[46:49]
	v_mfma_f32_16x16x32_bf16 v[38:41], v[162:165], v[178:181], v[38:41]
	v_mfma_f32_16x16x32_bf16 v[30:33], v[154:157], v[186:189], v[30:33]
	v_mfma_f32_16x16x32_bf16 v[22:25], v[162:165], v[186:189], v[22:25]
	v_mfma_f32_16x16x32_bf16 v[14:17], v[154:157], v[194:197], v[14:17]
	v_mfma_f32_16x16x32_bf16 v[6:9], v[162:165], v[194:197], v[6:9]
	s_barrier
	s_branch .Lpeel1_p3

.Lpeel1_p3:
	ds_read_b128 v[166:169], v229 offset:32768
	ds_read_b128 v[170:173], v229 offset:33792
	ds_read_b128 v[174:177], v229 offset:34816
	ds_read_b128 v[178:181], v229 offset:35840
	ds_read_b128 v[182:185], v229 offset:36864
	ds_read_b128 v[186:189], v229 offset:37888
	ds_read_b128 v[190:193], v229 offset:38912
	ds_read_b128 v[194:197], v229 offset:39936
	v_add_u32_e32 v134, 0x18000, v225
	v_add_u32_e32 v146, 0x1c000, v225
	ds_read_b128 v[150:153], v134
	ds_read_b128 v[154:157], v134 offset:1024
	ds_read_b128 v[158:161], v134 offset:2048
	ds_read_b128 v[162:165], v134 offset:3072
	ds_read_b128 v[134:137], v146
	ds_read_b128 v[138:141], v146 offset:1024
	ds_read_b128 v[142:145], v146 offset:2048
	ds_read_b128 v[146:149], v146 offset:3072
	s_add_i32 s62, 0, 0x18000
	s_add_i32 s63, 0, 0x1c000
	s_add_u32 s48, s48, 0x40000
	s_addc_u32 s49, s49, 0
	s_mov_b32 m0, s42
	s_nop 0
	global_load_lds_dwordx4 v204, s[48:49]
	s_mov_b32 m0, s43
	s_nop 0
	global_load_lds_dwordx4 v200, s[48:49]
	s_waitcnt vmcnt(8) lgkmcnt(0)
	s_barrier
	v_mfma_f32_16x16x32_bf16 v[130:133], v[150:153], v[166:169], v[130:133]
	v_mfma_f32_16x16x32_bf16 v[122:125], v[158:161], v[166:169], v[122:125]
	v_mfma_f32_16x16x32_bf16 v[114:117], v[150:153], v[174:177], v[114:117]
	v_mfma_f32_16x16x32_bf16 v[106:109], v[158:161], v[174:177], v[106:109]
	v_mfma_f32_16x16x32_bf16 v[98:101], v[150:153], v[182:185], v[98:101]
	v_mfma_f32_16x16x32_bf16 v[90:93], v[158:161], v[182:185], v[90:93]
	v_mfma_f32_16x16x32_bf16 v[82:85], v[150:153], v[190:193], v[82:85]
	v_mfma_f32_16x16x32_bf16 v[74:77], v[158:161], v[190:193], v[74:77]
	v_mfma_f32_16x16x32_bf16 v[130:133], v[154:157], v[170:173], v[130:133]
	v_mfma_f32_16x16x32_bf16 v[122:125], v[162:165], v[170:173], v[122:125]
	v_mfma_f32_16x16x32_bf16 v[114:117], v[154:157], v[178:181], v[114:117]
	v_mfma_f32_16x16x32_bf16 v[106:109], v[162:165], v[178:181], v[106:109]
	v_mfma_f32_16x16x32_bf16 v[98:101], v[154:157], v[186:189], v[98:101]
	v_mfma_f32_16x16x32_bf16 v[90:93], v[162:165], v[186:189], v[90:93]
	v_mfma_f32_16x16x32_bf16 v[82:85], v[154:157], v[194:197], v[82:85]
	v_mfma_f32_16x16x32_bf16 v[74:77], v[162:165], v[194:197], v[74:77]
	v_mfma_f32_16x16x32_bf16 v[126:129], v[134:137], v[166:169], v[126:129]
	v_mfma_f32_16x16x32_bf16 v[118:121], v[142:145], v[166:169], v[118:121]
	v_mfma_f32_16x16x32_bf16 v[110:113], v[134:137], v[174:177], v[110:113]
	v_mfma_f32_16x16x32_bf16 v[102:105], v[142:145], v[174:177], v[102:105]
	v_mfma_f32_16x16x32_bf16 v[94:97], v[134:137], v[182:185], v[94:97]
	v_mfma_f32_16x16x32_bf16 v[86:89], v[142:145], v[182:185], v[86:89]
	v_mfma_f32_16x16x32_bf16 v[78:81], v[134:137], v[190:193], v[78:81]
	v_mfma_f32_16x16x32_bf16 v[70:73], v[142:145], v[190:193], v[70:73]
	v_mfma_f32_16x16x32_bf16 v[126:129], v[138:141], v[170:173], v[126:129]
	v_mfma_f32_16x16x32_bf16 v[118:121], v[146:149], v[170:173], v[118:121]
	v_mfma_f32_16x16x32_bf16 v[110:113], v[138:141], v[178:181], v[110:113]
	v_mfma_f32_16x16x32_bf16 v[102:105], v[146:149], v[178:181], v[102:105]
	v_mfma_f32_16x16x32_bf16 v[94:97], v[138:141], v[186:189], v[94:97]
	v_mfma_f32_16x16x32_bf16 v[86:89], v[146:149], v[186:189], v[86:89]
	v_mfma_f32_16x16x32_bf16 v[78:81], v[138:141], v[194:197], v[78:81]
	v_mfma_f32_16x16x32_bf16 v[70:73], v[146:149], v[194:197], v[70:73]
	s_barrier
	ds_read_b128 v[190:193], v229 offset:49152
	ds_read_b128 v[194:197], v229 offset:50176
	ds_read_b128 v[182:185], v229 offset:51200
	ds_read_b128 v[186:189], v229 offset:52224
	ds_read_b128 v[174:177], v229 offset:53248
	ds_read_b128 v[178:181], v229 offset:54272
	ds_read_b128 v[166:169], v229 offset:55296
	ds_read_b128 v[170:173], v229 offset:56320
	s_add_i32 s48, s62, s12
	s_mov_b32 m0, s48
	s_nop 0
	global_load_lds_dwordx4 v202, s[98:99]
	s_add_i32 m0, s48, 0x2000
	s_add_u32 s46, s46, 0x40080
	s_addc_u32 s47, s47, 0
	s_add_i32 s48, s63, s12
	global_load_lds_dwordx4 v198, s[98:99]
	s_mov_b32 m0, s48
	s_andn2_b64 vcc, exec, s[30:31]
	global_load_lds_dwordx4 v202, s[46:47]
	s_add_i32 m0, s48, 0x2000
	s_nop 0
	global_load_lds_dwordx4 v198, s[46:47]
	s_mov_b32 m0, s51
	s_nop 0
	global_load_lds_dwordx4 v204, s[100:101]
	s_mov_b32 m0, s52
	s_nop 0
	global_load_lds_dwordx4 v200, s[100:101]
	s_waitcnt vmcnt(8)
	s_cbranch_vccnz .LBB0_329
	s_and_saveexec_b64 s[30:31], s[4:5]
	s_cbranch_execz .LBB0_328
	v_mov_b32_e32 v232, v3
	v_mov_b32_e32 v233, v4
	v_mov_b32_e32 v234, v2
	v_mov_b32_e32 v235, v5
	v_pk_add_f32 v[232:233], v[232:233], v[234:235]
	s_nop 0
	v_add_f32_e32 v226, v232, v233
	v_fmamk_f32 v226, v226, 0x3a800000, v230
	ds_write_b32 v228, v226
	s_branch .LBB0_328

.LBB0_1763:
	s_ashr_i32 s23, s22, 31
	s_lshl_b64 s[24:25], s[22:23], 19
	s_add_u32 s24, s68, s24
	s_addc_u32 s25, s69, s25
	s_and_b64 s[26:27], s[6:7], exec
	s_cselect_b32 s23, s25, s47
	s_cselect_b32 s56, s24, s46
	s_ashr_i32 s21, s20, 31
	s_lshl_b64 s[26:27], s[20:21], 19
	s_add_u32 s26, s0, s26
	s_addc_u32 s27, s1, s27
	s_and_b64 s[48:49], s[6:7], exec
	s_cselect_b32 s57, s27, s31
	s_cselect_b32 s58, s26, s30
	s_lshl_b32 s21, s28, 8
	v_add_u32_e32 v6, s21, v218
	s_add_u32 s28, s46, 0x40080
	v_ashrrev_i32_e32 v7, 31, v6
	s_addc_u32 s29, s47, 0
	v_lshl_add_u64 v[214:215], v[6:7], 4, s[8:9]
	s_add_u32 s59, s30, 0x100
	s_addc_u32 s60, s31, 0
	s_mov_b32 s61, -2
	s_cmp_eq_u32 s61, 12
	s_cselect_b64 s[30:31], -1, 0
	s_cmp_lg_u32 s61, 12
	s_cbranch_scc1 .Lpeel8_1768
	global_load_dwordx4 v[2:5], v[214:215], off
.Lpeel8_1768:
	v_add_u32_e32 v146, s53, v217
	v_add_u32_e32 v162, s54, v217
	ds_read_b128 v[134:137], v146
	ds_read_b128 v[138:141], v146 offset:1024
	ds_read_b128 v[142:145], v146 offset:2048
	ds_read_b128 v[146:149], v146 offset:3072
	ds_read_b128 v[150:153], v162
	ds_read_b128 v[154:157], v162 offset:1024
	ds_read_b128 v[158:161], v162 offset:2048
	ds_read_b128 v[162:165], v162 offset:3072
	s_add_u32 s48, s28, 0xfffc0080
	s_addc_u32 s49, s29, -1
	s_and_b64 s[46:47], s[30:31], exec
	s_cselect_b32 s49, s23, s49
	s_cselect_b32 s48, s56, s48
	s_cselect_b32 s47, s57, s60
	s_cselect_b32 s46, s58, s59
	s_add_i32 m0, s40, 0xc000
	ds_read_b128 v[166:169], v220
	ds_read_b128 v[170:173], v220 offset:1024
	ds_read_b128 v[174:177], v220 offset:2048
	ds_read_b128 v[178:181], v220 offset:3072
	ds_read_b128 v[182:185], v220 offset:4096
	ds_read_b128 v[186:189], v220 offset:5120
	ds_read_b128 v[190:193], v220 offset:6144
	ds_read_b128 v[194:197], v220 offset:7168
	global_load_lds_dwordx4 v206, s[28:29]
	s_add_i32 m0, s40, 0xe000
	s_nop 0
	global_load_lds_dwordx4 v208, s[28:29]
	s_waitcnt vmcnt(8) lgkmcnt(0)
	s_barrier
	v_mfma_f32_16x16x32_bf16 v[130:133], v[134:137], v[166:169], 0
	v_mfma_f32_16x16x32_bf16 v[122:125], v[142:145], v[166:169], 0
	v_mfma_f32_16x16x32_bf16 v[114:117], v[134:137], v[174:177], 0
	v_mfma_f32_16x16x32_bf16 v[106:109], v[142:145], v[174:177], 0
	v_mfma_f32_16x16x32_bf16 v[98:101], v[134:137], v[182:185], 0
	v_mfma_f32_16x16x32_bf16 v[90:93], v[142:145], v[182:185], 0
	v_mfma_f32_16x16x32_bf16 v[82:85], v[134:137], v[190:193], 0
	v_mfma_f32_16x16x32_bf16 v[74:77], v[142:145], v[190:193], 0
	v_mfma_f32_16x16x32_bf16 v[130:133], v[138:141], v[170:173], v[130:133]
	v_mfma_f32_16x16x32_bf16 v[122:125], v[146:149], v[170:173], v[122:125]
	v_mfma_f32_16x16x32_bf16 v[114:117], v[138:141], v[178:181], v[114:117]
	v_mfma_f32_16x16x32_bf16 v[106:109], v[146:149], v[178:181], v[106:109]
	v_mfma_f32_16x16x32_bf16 v[98:101], v[138:141], v[186:189], v[98:101]
	v_mfma_f32_16x16x32_bf16 v[90:93], v[146:149], v[186:189], v[90:93]
	v_mfma_f32_16x16x32_bf16 v[82:85], v[138:141], v[194:197], v[82:85]
	v_mfma_f32_16x16x32_bf16 v[74:77], v[146:149], v[194:197], v[74:77]
	v_mfma_f32_16x16x32_bf16 v[126:129], v[150:153], v[166:169], 0
	v_mfma_f32_16x16x32_bf16 v[118:121], v[158:161], v[166:169], 0
	v_mfma_f32_16x16x32_bf16 v[110:113], v[150:153], v[174:177], 0
	v_mfma_f32_16x16x32_bf16 v[102:105], v[158:161], v[174:177], 0
	v_mfma_f32_16x16x32_bf16 v[94:97], v[150:153], v[182:185], 0
	v_mfma_f32_16x16x32_bf16 v[86:89], v[158:161], v[182:185], 0
	v_mfma_f32_16x16x32_bf16 v[78:81], v[150:153], v[190:193], 0
	v_mfma_f32_16x16x32_bf16 v[70:73], v[158:161], v[190:193], 0
	v_mfma_f32_16x16x32_bf16 v[126:129], v[154:157], v[170:173], v[126:129]
	v_mfma_f32_16x16x32_bf16 v[118:121], v[162:165], v[170:173], v[118:121]
	v_mfma_f32_16x16x32_bf16 v[110:113], v[154:157], v[178:181], v[110:113]
	v_mfma_f32_16x16x32_bf16 v[102:105], v[162:165], v[178:181], v[102:105]
	v_mfma_f32_16x16x32_bf16 v[94:97], v[154:157], v[186:189], v[94:97]
	v_mfma_f32_16x16x32_bf16 v[86:89], v[162:165], v[186:189], v[86:89]
	v_mfma_f32_16x16x32_bf16 v[78:81], v[154:157], v[194:197], v[78:81]
	v_mfma_f32_16x16x32_bf16 v[70:73], v[162:165], v[194:197], v[70:73]
	s_barrier
	s_add_i32 s62, s53, s12
	s_add_u32 s98, s46, s16
	s_addc_u32 s99, s47, s17
	s_mov_b32 m0, s62
	ds_read_b128 v[166:169], v220 offset:16384
	ds_read_b128 v[170:173], v220 offset:17408
	ds_read_b128 v[174:177], v220 offset:18432
	ds_read_b128 v[178:181], v220 offset:19456
	ds_read_b128 v[182:185], v220 offset:20480
	ds_read_b128 v[186:189], v220 offset:21504
	ds_read_b128 v[190:193], v220 offset:22528
	ds_read_b128 v[194:197], v220 offset:23552
	global_load_lds_dwordx4 v202, s[46:47]
	s_add_i32 m0, s62, 0x2000
	s_add_u32 s62, s46, 0x40000
	s_addc_u32 s63, s47, 0
	s_add_i32 s64, s54, s12
	global_load_lds_dwordx4 v198, s[46:47]
	s_mov_b32 m0, s64
	s_nop 0
	global_load_lds_dwordx4 v202, s[62:63]
	s_add_i32 m0, s64, 0x2000
	s_nop 0
	global_load_lds_dwordx4 v198, s[62:63]
	s_add_u32 s100, s48, s16
	s_addc_u32 s101, s49, s17
	s_mov_b32 m0, s40
	s_nop 0
	global_load_lds_dwordx4 v204, s[48:49]
	s_mov_b32 m0, s41
	s_nop 0
	global_load_lds_dwordx4 v200, s[48:49]
	s_waitcnt vmcnt(8) lgkmcnt(0)
	s_barrier
	v_mfma_f32_16x16x32_bf16 v[66:69], v[134:137], v[166:169], 0
	v_mfma_f32_16x16x32_bf16 v[58:61], v[142:145], v[166:169], 0
	v_mfma_f32_16x16x32_bf16 v[50:53], v[134:137], v[174:177], 0
	v_mfma_f32_16x16x32_bf16 v[42:45], v[142:145], v[174:177], 0
	v_mfma_f32_16x16x32_bf16 v[34:37], v[134:137], v[182:185], 0
	v_mfma_f32_16x16x32_bf16 v[26:29], v[142:145], v[182:185], 0
	v_mfma_f32_16x16x32_bf16 v[18:21], v[134:137], v[190:193], 0
	v_mfma_f32_16x16x32_bf16 v[10:13], v[142:145], v[190:193], 0
	v_mfma_f32_16x16x32_bf16 v[66:69], v[138:141], v[170:173], v[66:69]
	v_mfma_f32_16x16x32_bf16 v[58:61], v[146:149], v[170:173], v[58:61]
	v_mfma_f32_16x16x32_bf16 v[50:53], v[138:141], v[178:181], v[50:53]
	v_mfma_f32_16x16x32_bf16 v[42:45], v[146:149], v[178:181], v[42:45]
	v_mfma_f32_16x16x32_bf16 v[34:37], v[138:141], v[186:189], v[34:37]
	v_mfma_f32_16x16x32_bf16 v[26:29], v[146:149], v[186:189], v[26:29]
	v_mfma_f32_16x16x32_bf16 v[18:21], v[138:141], v[194:197], v[18:21]
	v_mfma_f32_16x16x32_bf16 v[10:13], v[146:149], v[194:197], v[10:13]
	v_mfma_f32_16x16x32_bf16 v[62:65], v[150:153], v[166:169], 0
	v_mfma_f32_16x16x32_bf16 v[54:57], v[158:161], v[166:169], 0
	v_mfma_f32_16x16x32_bf16 v[46:49], v[150:153], v[174:177], 0
	v_mfma_f32_16x16x32_bf16 v[38:41], v[158:161], v[174:177], 0
	v_mfma_f32_16x16x32_bf16 v[30:33], v[150:153], v[182:185], 0
	v_mfma_f32_16x16x32_bf16 v[22:25], v[158:161], v[182:185], 0
	v_mfma_f32_16x16x32_bf16 v[14:17], v[150:153], v[190:193], 0
	v_mfma_f32_16x16x32_bf16 v[6:9], v[158:161], v[190:193], 0
	v_mfma_f32_16x16x32_bf16 v[62:65], v[154:157], v[170:173], v[62:65]
	v_mfma_f32_16x16x32_bf16 v[54:57], v[162:165], v[170:173], v[54:57]
	v_mfma_f32_16x16x32_bf16 v[46:49], v[154:157], v[178:181], v[46:49]
	v_mfma_f32_16x16x32_bf16 v[38:41], v[162:165], v[178:181], v[38:41]
	v_mfma_f32_16x16x32_bf16 v[30:33], v[154:157], v[186:189], v[30:33]
	v_mfma_f32_16x16x32_bf16 v[22:25], v[162:165], v[186:189], v[22:25]
	v_mfma_f32_16x16x32_bf16 v[14:17], v[154:157], v[194:197], v[14:17]
	v_mfma_f32_16x16x32_bf16 v[6:9], v[162:165], v[194:197], v[6:9]
	s_barrier
	s_branch .Lpeel8_p3

.Lpeel8_p3:
	s_add_i32 s62, 0, 0x18000
	s_add_i32 s63, 0, 0x1c000
	v_add_u32_e32 v134, s62, v217
	v_add_u32_e32 v146, s63, v217
	ds_read_b128 v[150:153], v134
	ds_read_b128 v[154:157], v134 offset:1024
	ds_read_b128 v[158:161], v134 offset:2048
	ds_read_b128 v[162:165], v134 offset:3072
	ds_read_b128 v[134:137], v146
	ds_read_b128 v[138:141], v146 offset:1024
	ds_read_b128 v[142:145], v146 offset:2048
	ds_read_b128 v[146:149], v146 offset:3072
	s_add_u32 s48, s48, 0x40000
	s_addc_u32 s49, s49, 0
	s_mov_b32 m0, s42
	ds_read_b128 v[166:169], v220 offset:32768
	ds_read_b128 v[170:173], v220 offset:33792
	ds_read_b128 v[174:177], v220 offset:34816
	ds_read_b128 v[178:181], v220 offset:35840
	ds_read_b128 v[182:185], v220 offset:36864
	ds_read_b128 v[186:189], v220 offset:37888
	ds_read_b128 v[190:193], v220 offset:38912
	ds_read_b128 v[194:197], v220 offset:39936
	global_load_lds_dwordx4 v204, s[48:49]
	s_mov_b32 m0, s43
	s_nop 0
	global_load_lds_dwordx4 v200, s[48:49]
	s_waitcnt vmcnt(8) lgkmcnt(0)
	s_barrier
	v_mfma_f32_16x16x32_bf16 v[130:133], v[150:153], v[166:169], v[130:133]
	v_mfma_f32_16x16x32_bf16 v[122:125], v[158:161], v[166:169], v[122:125]
	v_mfma_f32_16x16x32_bf16 v[114:117], v[150:153], v[174:177], v[114:117]
	v_mfma_f32_16x16x32_bf16 v[106:109], v[158:161], v[174:177], v[106:109]
	v_mfma_f32_16x16x32_bf16 v[98:101], v[150:153], v[182:185], v[98:101]
	v_mfma_f32_16x16x32_bf16 v[90:93], v[158:161], v[182:185], v[90:93]
	v_mfma_f32_16x16x32_bf16 v[82:85], v[150:153], v[190:193], v[82:85]
	v_mfma_f32_16x16x32_bf16 v[74:77], v[158:161], v[190:193], v[74:77]
	v_mfma_f32_16x16x32_bf16 v[130:133], v[154:157], v[170:173], v[130:133]
	v_mfma_f32_16x16x32_bf16 v[122:125], v[162:165], v[170:173], v[122:125]
	v_mfma_f32_16x16x32_bf16 v[114:117], v[154:157], v[178:181], v[114:117]
	v_mfma_f32_16x16x32_bf16 v[106:109], v[162:165], v[178:181], v[106:109]
	v_mfma_f32_16x16x32_bf16 v[98:101], v[154:157], v[186:189], v[98:101]
	v_mfma_f32_16x16x32_bf16 v[90:93], v[162:165], v[186:189], v[90:93]
	v_mfma_f32_16x16x32_bf16 v[82:85], v[154:157], v[194:197], v[82:85]
	v_mfma_f32_16x16x32_bf16 v[74:77], v[162:165], v[194:197], v[74:77]
	v_mfma_f32_16x16x32_bf16 v[126:129], v[134:137], v[166:169], v[126:129]
	v_mfma_f32_16x16x32_bf16 v[118:121], v[142:145], v[166:169], v[118:121]
	v_mfma_f32_16x16x32_bf16 v[110:113], v[134:137], v[174:177], v[110:113]
	v_mfma_f32_16x16x32_bf16 v[102:105], v[142:145], v[174:177], v[102:105]
	v_mfma_f32_16x16x32_bf16 v[94:97], v[134:137], v[182:185], v[94:97]
	v_mfma_f32_16x16x32_bf16 v[86:89], v[142:145], v[182:185], v[86:89]
	v_mfma_f32_16x16x32_bf16 v[78:81], v[134:137], v[190:193], v[78:81]
	v_mfma_f32_16x16x32_bf16 v[70:73], v[142:145], v[190:193], v[70:73]
	v_mfma_f32_16x16x32_bf16 v[126:129], v[138:141], v[170:173], v[126:129]
	v_mfma_f32_16x16x32_bf16 v[118:121], v[146:149], v[170:173], v[118:121]
	v_mfma_f32_16x16x32_bf16 v[110:113], v[138:141], v[178:181], v[110:113]
	v_mfma_f32_16x16x32_bf16 v[102:105], v[146:149], v[178:181], v[102:105]
	v_mfma_f32_16x16x32_bf16 v[94:97], v[138:141], v[186:189], v[94:97]
	v_mfma_f32_16x16x32_bf16 v[86:89], v[146:149], v[186:189], v[86:89]
	v_mfma_f32_16x16x32_bf16 v[78:81], v[138:141], v[194:197], v[78:81]
	v_mfma_f32_16x16x32_bf16 v[70:73], v[146:149], v[194:197], v[70:73]
	s_barrier
	s_add_i32 s48, s62, s12
	s_mov_b32 m0, s48
	ds_read_b128 v[190:193], v220 offset:49152
	ds_read_b128 v[194:197], v220 offset:50176
	ds_read_b128 v[182:185], v220 offset:51200
	ds_read_b128 v[186:189], v220 offset:52224
	ds_read_b128 v[174:177], v220 offset:53248
	ds_read_b128 v[178:181], v220 offset:54272
	ds_read_b128 v[166:169], v220 offset:55296
	ds_read_b128 v[170:173], v220 offset:56320
	global_load_lds_dwordx4 v202, s[98:99]
	s_add_i32 m0, s48, 0x2000
	s_add_u32 s46, s46, 0x40080
	s_addc_u32 s47, s47, 0
	s_add_i32 s48, s63, s12
	global_load_lds_dwordx4 v198, s[98:99]
	s_mov_b32 m0, s48
	s_andn2_b64 vcc, exec, s[30:31]
	global_load_lds_dwordx4 v202, s[46:47]
	s_add_i32 m0, s48, 0x2000
	s_nop 0
	global_load_lds_dwordx4 v198, s[46:47]
	s_mov_b32 m0, s51
	s_nop 0
	global_load_lds_dwordx4 v204, s[100:101]
	s_mov_b32 m0, s52
	s_nop 0
	global_load_lds_dwordx4 v200, s[100:101]
	s_waitcnt vmcnt(8)
	s_cbranch_vccnz .LBB0_1765
	s_and_saveexec_b64 s[30:31], s[4:5]
	s_cbranch_execz .LBB0_1764
	v_mov_b32_e32 v222, v3
	v_mov_b32_e32 v223, v4
	v_mov_b32_e32 v224, v2
	v_mov_b32_e32 v225, v5
	v_pk_add_f32 v[222:223], v[222:223], v[224:225]
	s_nop 0
	v_add_f32_e32 v222, v222, v223
	v_fmamk_f32 v222, v222, 0x3a800000, v221
	ds_write_b32 v219, v222
	s_branch .LBB0_1764
